# strategy 7+10: S1 l2norm rsq denormal rescue removed (x+1e-6 is never subnormal), on top of phase-5 residual cache touch during the K loop and S1 store-address immediates
# speedup vs baseline: 1.0166x; 1.0046x over previous
.Lp3a_s2h_skip:
	v_pk_fma_f32 v[52:53], v[110:111], v[48:49], v[52:53]
	v_pk_add_f32 v[226:227], v[226:227], 1.0 op_sel_hi:[1,0]
	v_pk_mul_f32 v[228:229], v[52:53], v[246:247] op_sel_hi:[1,0]
	v_rcp_f32_e32 v226, v226
	v_rcp_f32_e32 v227, v227
	v_exp_f32_e32 v228, v228
	v_exp_f32_e32 v229, v229
	v_lshlrev_b32_e32 v28, 16, v121
	v_pk_mul_f32 v[22:23], v[22:23], v[226:227]
	v_pk_add_f32 v[228:229], v[228:229], 1.0 op_sel_hi:[1,0]
	v_lshlrev_b32_e32 v54, 16, v117
	v_and_b32_e32 v55, 0xffff0000, v117
	v_and_b32_e32 v29, 0xffff0000, v121
	v_pk_fma_f32 v[54:55], v[4:5], v[54:55], 0 op_sel_hi:[1,1,0]
	v_lshlrev_b32_e32 v36, 16, v125
	v_and_b32_e32 v37, 0xffff0000, v125
	v_pk_fma_f32 v[54:55], v[16:17], v[28:29], v[54:55]
	v_lshlrev_b32_e32 v44, 16, v129
	v_and_b32_e32 v45, 0xffff0000, v129
	v_pk_fma_f32 v[54:55], v[104:105], v[36:37], v[54:55]
	v_rcp_f32_e32 v228, v228
	v_pk_fma_f32 v[54:55], v[112:113], v[44:45], v[54:55]
	v_rcp_f32_e32 v229, v229
	v_pk_mul_f32 v[226:227], v[54:55], v[246:247] op_sel_hi:[1,0]
	v_exp_f32_e32 v226, v226
	v_exp_f32_e32 v227, v227
	v_pk_mul_f32 v[232:233], v[20:21], v[20:21]
	v_pk_fma_f32 v[232:233], v[22:23], v[22:23], v[232:233]
	v_pk_add_f32 v[226:227], v[226:227], 1.0 op_sel_hi:[1,0]
	v_rcp_f32_e32 v226, v226
	v_rcp_f32_e32 v227, v227
	v_pk_mul_f32 v[52:53], v[52:53], v[228:229]
	v_and_b32_e32 v167, 64, v184
	v_pk_fma_f32 v[232:233], v[52:53], v[52:53], v[232:233]
	v_pk_mul_f32 v[54:55], v[54:55], v[226:227]
	v_pk_fma_f32 v[232:233], v[54:55], v[54:55], v[232:233]
	v_add_f32_e32 v24, v232, v233
	v_mov_b32_e32 v160, v1
	s_nop 1
	v_add_f32_dpp v24, v24, v24 quad_perm:[1,0,3,2] row_mask:0xf bank_mask:0xf
	v_cmp_gt_i32_e64 s[6:7], 16, v160
	v_mov_b32_e32 v56, 1.0
	s_nop 1
	v_add_f32_dpp v24, v24, v24 quad_perm:[2,3,0,1] row_mask:0xf bank_mask:0xf
	v_cndmask_b32_e64 v161, 1.0, v187, s[6:7]
	v_cmp_gt_i32_e64 s[4:5], 32, v160
	s_nop 1
	v_add_f32_dpp v24, v24, v24 row_half_mirror row_mask:0xf bank_mask:0xf
	s_nop 1
	v_add_f32_dpp v24, v24, v24 row_mirror row_mask:0xf bank_mask:0xf
	s_and_saveexec_b64 s[8:9], s[4:5]
	s_cbranch_execz .LBB0_502
	v_add_f32_e32 v24, 0x358637bd, v24
	v_rsq_f32_e32 v24, v24
	s_nop 0
	v_mul_f32_e32 v56, v161, v24

.LBB0_504:
	s_or_b64 exec, exec, s[8:9]
	v_pk_fma_f32 v[34:35], v[6:7], v[34:35], 0 op_sel_hi:[1,1,0]
	v_lshlrev_b32_e32 v60, 16, v130
	v_pk_fma_f32 v[34:35], v[10:11], v[42:43], v[34:35]
	v_and_b32_e32 v61, 0xffff0000, v130
	v_pk_fma_f32 v[34:35], v[98:99], v[50:51], v[34:35]
	v_pk_fma_f32 v[32:33], v[8:9], v[32:33], 0 op_sel_hi:[1,1,0]
	v_pk_fma_f32 v[34:35], v[106:107], v[60:61], v[34:35]
	v_pk_fma_f32 v[32:33], v[12:13], v[40:41], v[32:33]
	v_pk_mul_f32 v[226:227], v[34:35], v[246:247] op_sel_hi:[1,0]
	v_exp_f32_e32 v226, v226
	v_exp_f32_e32 v227, v227
	v_lshlrev_b32_e32 v58, 16, v131
	v_and_b32_e32 v59, 0xffff0000, v131
	v_pk_add_f32 v[226:227], v[226:227], 1.0 op_sel_hi:[1,0]
	v_rcp_f32_e32 v226, v226
	v_rcp_f32_e32 v227, v227
	v_pk_fma_f32 v[32:33], v[100:101], v[46:47], v[32:33]
	v_pk_fma_f32 v[30:31], v[2:3], v[30:31], 0 op_sel_hi:[1,1,0]
	v_pk_fma_f32 v[32:33], v[108:109], v[58:59], v[32:33]
	v_pk_mul_f32 v[34:35], v[34:35], v[226:227]
	v_pk_mul_f32 v[226:227], v[32:33], v[246:247] op_sel_hi:[1,0]
	v_exp_f32_e32 v226, v226
	v_exp_f32_e32 v227, v227
	v_pk_fma_f32 v[30:31], v[14:15], v[38:39], v[30:31]
	v_lshlrev_b32_e32 v62, 16, v132
	v_pk_add_f32 v[226:227], v[226:227], 1.0 op_sel_hi:[1,0]
	v_and_b32_e32 v63, 0xffff0000, v132
	v_rcp_f32_e32 v226, v226
	v_rcp_f32_e32 v227, v227
	v_pk_fma_f32 v[30:31], v[102:103], v[48:49], v[30:31]
	v_pk_fma_f32 v[28:29], v[4:5], v[28:29], 0 op_sel_hi:[1,1,0]
	v_pk_fma_f32 v[64:65], v[110:111], v[62:63], v[30:31]
	v_pk_fma_f32 v[28:29], v[16:17], v[36:37], v[28:29]
	v_pk_mul_f32 v[228:229], v[64:65], v[246:247] op_sel_hi:[1,0]
	v_lshlrev_b32_e32 v56, 16, v133
	v_and_b32_e32 v57, 0xffff0000, v133
	v_exp_f32_e32 v228, v228
	v_pk_fma_f32 v[28:29], v[104:105], v[44:45], v[28:29]
	v_exp_f32_e32 v229, v229
	v_pk_mul_f32 v[30:31], v[32:33], v[226:227]
	v_pk_fma_f32 v[52:53], v[112:113], v[56:57], v[28:29]
	v_pk_mul_f32 v[226:227], v[52:53], v[246:247] op_sel_hi:[1,0]
	v_exp_f32_e32 v226, v226
	v_exp_f32_e32 v227, v227
	v_pk_add_f32 v[228:229], v[228:229], 1.0 op_sel_hi:[1,0]
	v_rcp_f32_e32 v228, v228
	v_rcp_f32_e32 v229, v229
	v_pk_add_f32 v[226:227], v[226:227], 1.0 op_sel_hi:[1,0]
	v_rcp_f32_e32 v226, v226
	v_pk_mul_f32 v[234:235], v[34:35], v[34:35]
	v_rcp_f32_e32 v227, v227
	v_pk_fma_f32 v[234:235], v[30:31], v[30:31], v[234:235]
	v_pk_mul_f32 v[28:29], v[64:65], v[228:229]
	v_pk_fma_f32 v[234:235], v[28:29], v[28:29], v[234:235]
	v_pk_mul_f32 v[52:53], v[52:53], v[226:227]
	v_pk_fma_f32 v[234:235], v[52:53], v[52:53], v[234:235]
	v_add_f32_e32 v32, v234, v235
	v_mov_b32_e32 v54, 1.0
	s_nop 1
	v_add_f32_dpp v32, v32, v32 quad_perm:[1,0,3,2] row_mask:0xf bank_mask:0xf
	s_nop 1
	v_add_f32_dpp v32, v32, v32 quad_perm:[2,3,0,1] row_mask:0xf bank_mask:0xf
	s_nop 1
	v_add_f32_dpp v32, v32, v32 row_half_mirror row_mask:0xf bank_mask:0xf
	s_nop 1
	v_add_f32_dpp v32, v32, v32 row_mirror row_mask:0xf bank_mask:0xf
	s_and_saveexec_b64 s[8:9], s[4:5]
	s_cbranch_execz .LBB0_506
	v_add_f32_e32 v32, 0x358637bd, v32
	v_rsq_f32_e32 v32, v32
	s_nop 0
	v_mul_f32_e32 v54, v161, v32

.LBB0_508:
	s_or_b64 exec, exec, s[8:9]
	v_pk_fma_f32 v[42:43], v[6:7], v[42:43], 0 op_sel_hi:[1,1,0]
	v_lshlrev_b32_e32 v80, 16, v134
	v_pk_fma_f32 v[42:43], v[10:11], v[50:51], v[42:43]
	v_and_b32_e32 v81, 0xffff0000, v134
	v_pk_fma_f32 v[42:43], v[98:99], v[60:61], v[42:43]
	v_pk_fma_f32 v[40:41], v[8:9], v[40:41], 0 op_sel_hi:[1,1,0]
	v_pk_fma_f32 v[42:43], v[106:107], v[80:81], v[42:43]
	v_pk_fma_f32 v[40:41], v[12:13], v[46:47], v[40:41]
	v_pk_mul_f32 v[226:227], v[42:43], v[246:247] op_sel_hi:[1,0]
	v_exp_f32_e32 v226, v226
	v_exp_f32_e32 v227, v227
	v_lshlrev_b32_e32 v66, 16, v135
	v_and_b32_e32 v67, 0xffff0000, v135
	v_pk_add_f32 v[226:227], v[226:227], 1.0 op_sel_hi:[1,0]
	v_rcp_f32_e32 v226, v226
	v_rcp_f32_e32 v227, v227
	v_pk_fma_f32 v[40:41], v[100:101], v[58:59], v[40:41]
	v_pk_fma_f32 v[38:39], v[2:3], v[38:39], 0 op_sel_hi:[1,1,0]
	v_pk_fma_f32 v[40:41], v[108:109], v[66:67], v[40:41]
	v_pk_mul_f32 v[42:43], v[42:43], v[226:227]
	v_pk_mul_f32 v[226:227], v[40:41], v[246:247] op_sel_hi:[1,0]
	v_exp_f32_e32 v226, v226
	v_exp_f32_e32 v227, v227
	v_pk_fma_f32 v[38:39], v[14:15], v[48:49], v[38:39]
	v_lshlrev_b32_e32 v72, 16, v136
	v_pk_add_f32 v[226:227], v[226:227], 1.0 op_sel_hi:[1,0]
	v_and_b32_e32 v73, 0xffff0000, v136
	v_rcp_f32_e32 v226, v226
	v_rcp_f32_e32 v227, v227
	v_pk_fma_f32 v[38:39], v[102:103], v[62:63], v[38:39]
	v_pk_fma_f32 v[36:37], v[4:5], v[36:37], 0 op_sel_hi:[1,1,0]
	v_pk_fma_f32 v[68:69], v[110:111], v[72:73], v[38:39]
	v_pk_fma_f32 v[36:37], v[16:17], v[44:45], v[36:37]
	v_pk_mul_f32 v[228:229], v[68:69], v[246:247] op_sel_hi:[1,0]
	v_lshlrev_b32_e32 v54, 16, v137
	v_and_b32_e32 v55, 0xffff0000, v137
	v_exp_f32_e32 v228, v228
	v_pk_fma_f32 v[36:37], v[104:105], v[56:57], v[36:37]
	v_exp_f32_e32 v229, v229
	v_pk_mul_f32 v[38:39], v[40:41], v[226:227]
	v_pk_fma_f32 v[52:53], v[112:113], v[54:55], v[36:37]
	v_pk_mul_f32 v[226:227], v[52:53], v[246:247] op_sel_hi:[1,0]
	v_exp_f32_e32 v226, v226
	v_exp_f32_e32 v227, v227
	v_pk_add_f32 v[228:229], v[228:229], 1.0 op_sel_hi:[1,0]
	v_rcp_f32_e32 v228, v228
	v_rcp_f32_e32 v229, v229
	v_pk_add_f32 v[226:227], v[226:227], 1.0 op_sel_hi:[1,0]
	v_rcp_f32_e32 v226, v226
	v_pk_mul_f32 v[236:237], v[42:43], v[42:43]
	v_rcp_f32_e32 v227, v227
	v_pk_fma_f32 v[236:237], v[38:39], v[38:39], v[236:237]
	v_pk_mul_f32 v[36:37], v[68:69], v[228:229]
	v_pk_fma_f32 v[236:237], v[36:37], v[36:37], v[236:237]
	v_pk_mul_f32 v[52:53], v[52:53], v[226:227]
	v_pk_fma_f32 v[236:237], v[52:53], v[52:53], v[236:237]
	v_add_f32_e32 v40, v236, v237
	v_mov_b32_e32 v64, 1.0
	s_nop 1
	v_add_f32_dpp v40, v40, v40 quad_perm:[1,0,3,2] row_mask:0xf bank_mask:0xf
	s_nop 1
	v_add_f32_dpp v40, v40, v40 quad_perm:[2,3,0,1] row_mask:0xf bank_mask:0xf
	s_nop 1
	v_add_f32_dpp v40, v40, v40 row_half_mirror row_mask:0xf bank_mask:0xf
	s_nop 1
	v_add_f32_dpp v40, v40, v40 row_mirror row_mask:0xf bank_mask:0xf
	s_and_saveexec_b64 s[8:9], s[4:5]
	s_cbranch_execz .LBB0_510
	v_add_f32_e32 v40, 0x358637bd, v40
	v_rsq_f32_e32 v40, v40
	s_nop 0
	v_mul_f32_e32 v64, v161, v40

.LBB0_512:
	s_or_b64 exec, exec, s[8:9]
	v_pk_fma_f32 v[50:51], v[6:7], v[50:51], 0 op_sel_hi:[1,1,0]
	v_lshlrev_b32_e32 v78, 16, v138
	v_pk_fma_f32 v[50:51], v[10:11], v[60:61], v[50:51]
	v_and_b32_e32 v79, 0xffff0000, v138
	v_pk_fma_f32 v[50:51], v[98:99], v[80:81], v[50:51]
	v_pk_fma_f32 v[46:47], v[8:9], v[46:47], 0 op_sel_hi:[1,1,0]
	v_pk_fma_f32 v[50:51], v[106:107], v[78:79], v[50:51]
	v_pk_fma_f32 v[46:47], v[12:13], v[58:59], v[46:47]
	v_pk_mul_f32 v[226:227], v[50:51], v[246:247] op_sel_hi:[1,0]
	v_exp_f32_e32 v226, v226
	v_exp_f32_e32 v227, v227
	v_lshlrev_b32_e32 v64, 16, v139
	v_pk_add_f32 v[226:227], v[226:227], 1.0 op_sel_hi:[1,0]
	v_rcp_f32_e32 v226, v226
	v_rcp_f32_e32 v227, v227
	v_and_b32_e32 v65, 0xffff0000, v139
	v_pk_fma_f32 v[46:47], v[100:101], v[66:67], v[46:47]
	v_pk_fma_f32 v[48:49], v[2:3], v[48:49], 0 op_sel_hi:[1,1,0]
	v_pk_fma_f32 v[46:47], v[108:109], v[64:65], v[46:47]
	v_pk_mul_f32 v[50:51], v[50:51], v[226:227]
	v_pk_mul_f32 v[226:227], v[46:47], v[246:247] op_sel_hi:[1,0]
	v_exp_f32_e32 v226, v226
	v_exp_f32_e32 v227, v227
	v_pk_fma_f32 v[48:49], v[14:15], v[62:63], v[48:49]
	v_lshlrev_b32_e32 v70, 16, v140
	v_and_b32_e32 v71, 0xffff0000, v140
	v_pk_fma_f32 v[48:49], v[102:103], v[72:73], v[48:49]
	v_pk_fma_f32 v[48:49], v[110:111], v[70:71], v[48:49]
	v_pk_add_f32 v[226:227], v[226:227], 1.0 op_sel_hi:[1,0]
	v_pk_mul_f32 v[228:229], v[48:49], v[246:247] op_sel_hi:[1,0]
	v_rcp_f32_e32 v226, v226
	v_rcp_f32_e32 v227, v227
	v_exp_f32_e32 v228, v228
	v_exp_f32_e32 v229, v229
	v_pk_fma_f32 v[44:45], v[4:5], v[44:45], 0 op_sel_hi:[1,1,0]
	v_lshlrev_b32_e32 v52, 16, v141
	v_pk_fma_f32 v[44:45], v[16:17], v[56:57], v[44:45]
	v_and_b32_e32 v53, 0xffff0000, v141
	v_pk_fma_f32 v[44:45], v[104:105], v[54:55], v[44:45]
	v_pk_mul_f32 v[46:47], v[46:47], v[226:227]
	v_pk_add_f32 v[228:229], v[228:229], 1.0 op_sel_hi:[1,0]
	v_pk_fma_f32 v[76:77], v[112:113], v[52:53], v[44:45]
	v_rcp_f32_e32 v228, v228
	v_pk_mul_f32 v[226:227], v[76:77], v[246:247] op_sel_hi:[1,0]
	v_exp_f32_e32 v226, v226
	v_exp_f32_e32 v227, v227
	v_rcp_f32_e32 v229, v229
	v_pk_add_f32 v[226:227], v[226:227], 1.0 op_sel_hi:[1,0]
	v_rcp_f32_e32 v226, v226
	v_pk_mul_f32 v[238:239], v[50:51], v[50:51]
	v_rcp_f32_e32 v227, v227
	v_pk_fma_f32 v[238:239], v[46:47], v[46:47], v[238:239]
	v_pk_mul_f32 v[44:45], v[48:49], v[228:229]
	v_pk_fma_f32 v[238:239], v[44:45], v[44:45], v[238:239]
	v_pk_mul_f32 v[68:69], v[76:77], v[226:227]
	v_pk_fma_f32 v[238:239], v[68:69], v[68:69], v[238:239]
	v_add_f32_e32 v48, v238, v239
	v_mov_b32_e32 v74, 1.0
	s_nop 1
	v_add_f32_dpp v48, v48, v48 quad_perm:[1,0,3,2] row_mask:0xf bank_mask:0xf
	s_nop 1
	v_add_f32_dpp v48, v48, v48 quad_perm:[2,3,0,1] row_mask:0xf bank_mask:0xf
	s_nop 1
	v_add_f32_dpp v48, v48, v48 row_half_mirror row_mask:0xf bank_mask:0xf
	s_nop 1
	v_add_f32_dpp v48, v48, v48 row_mirror row_mask:0xf bank_mask:0xf
	s_and_saveexec_b64 s[8:9], s[4:5]
	s_cbranch_execz .LBB0_514
	v_add_f32_e32 v48, 0x358637bd, v48
	v_rsq_f32_e32 v48, v48
	s_nop 0
	v_mul_f32_e32 v74, v161, v48

.LBB0_516:
	s_or_b64 exec, exec, s[8:9]
	v_pk_fma_f32 v[60:61], v[6:7], v[60:61], 0 op_sel_hi:[1,1,0]
	v_lshlrev_b32_e32 v82, 16, v142
	v_pk_fma_f32 v[60:61], v[10:11], v[80:81], v[60:61]
	v_and_b32_e32 v83, 0xffff0000, v142
	v_pk_fma_f32 v[60:61], v[98:99], v[78:79], v[60:61]
	v_pk_fma_f32 v[58:59], v[8:9], v[58:59], 0 op_sel_hi:[1,1,0]
	v_pk_fma_f32 v[68:69], v[106:107], v[82:83], v[60:61]
	v_pk_fma_f32 v[58:59], v[12:13], v[66:67], v[58:59]
	v_pk_mul_f32 v[226:227], v[68:69], v[246:247] op_sel_hi:[1,0]
	v_exp_f32_e32 v226, v226
	v_exp_f32_e32 v227, v227
	v_lshlrev_b32_e32 v76, 16, v143
	v_pk_add_f32 v[226:227], v[226:227], 1.0 op_sel_hi:[1,0]
	v_rcp_f32_e32 v226, v226
	v_rcp_f32_e32 v227, v227
	v_and_b32_e32 v77, 0xffff0000, v143
	v_pk_fma_f32 v[58:59], v[100:101], v[64:65], v[58:59]
	v_pk_fma_f32 v[62:63], v[2:3], v[62:63], 0 op_sel_hi:[1,1,0]
	v_pk_fma_f32 v[58:59], v[108:109], v[76:77], v[58:59]
	v_pk_mul_f32 v[68:69], v[68:69], v[226:227]
	v_pk_mul_f32 v[226:227], v[58:59], v[246:247] op_sel_hi:[1,0]
	v_exp_f32_e32 v226, v226
	v_exp_f32_e32 v227, v227
	v_pk_fma_f32 v[62:63], v[14:15], v[72:73], v[62:63]
	v_lshlrev_b32_e32 v74, 16, v144
	v_and_b32_e32 v75, 0xffff0000, v144
	v_pk_fma_f32 v[62:63], v[102:103], v[70:71], v[62:63]
	v_pk_fma_f32 v[62:63], v[110:111], v[74:75], v[62:63]
	v_pk_add_f32 v[226:227], v[226:227], 1.0 op_sel_hi:[1,0]
	v_pk_mul_f32 v[228:229], v[62:63], v[246:247] op_sel_hi:[1,0]
	v_rcp_f32_e32 v226, v226
	v_rcp_f32_e32 v227, v227
	v_exp_f32_e32 v228, v228
	v_exp_f32_e32 v229, v229
	v_pk_fma_f32 v[56:57], v[4:5], v[56:57], 0 op_sel_hi:[1,1,0]
	v_lshlrev_b32_e32 v60, 16, v145
	v_pk_fma_f32 v[56:57], v[16:17], v[54:55], v[56:57]
	v_and_b32_e32 v61, 0xffff0000, v145
	v_pk_fma_f32 v[56:57], v[104:105], v[52:53], v[56:57]
	v_pk_mul_f32 v[58:59], v[58:59], v[226:227]
	v_pk_add_f32 v[228:229], v[228:229], 1.0 op_sel_hi:[1,0]
	v_pk_fma_f32 v[88:89], v[112:113], v[60:61], v[56:57]
	v_rcp_f32_e32 v228, v228
	v_pk_mul_f32 v[226:227], v[88:89], v[246:247] op_sel_hi:[1,0]
	v_exp_f32_e32 v226, v226
	v_exp_f32_e32 v227, v227
	v_rcp_f32_e32 v229, v229
	v_pk_add_f32 v[226:227], v[226:227], 1.0 op_sel_hi:[1,0]
	v_rcp_f32_e32 v226, v226
	v_pk_mul_f32 v[232:233], v[68:69], v[68:69]
	v_rcp_f32_e32 v227, v227
	v_pk_fma_f32 v[232:233], v[58:59], v[58:59], v[232:233]
	v_pk_mul_f32 v[56:57], v[62:63], v[228:229]
	v_pk_fma_f32 v[232:233], v[56:57], v[56:57], v[232:233]
	v_pk_mul_f32 v[84:85], v[88:89], v[226:227]
	v_pk_fma_f32 v[232:233], v[84:85], v[84:85], v[232:233]
	v_add_f32_e32 v62, v232, v233
	v_mov_b32_e32 v86, 1.0
	s_nop 1
	v_add_f32_dpp v62, v62, v62 quad_perm:[1,0,3,2] row_mask:0xf bank_mask:0xf
	s_nop 1
	v_add_f32_dpp v62, v62, v62 quad_perm:[2,3,0,1] row_mask:0xf bank_mask:0xf
	s_nop 1
	v_add_f32_dpp v62, v62, v62 row_half_mirror row_mask:0xf bank_mask:0xf
	s_nop 1
	v_add_f32_dpp v62, v62, v62 row_mirror row_mask:0xf bank_mask:0xf
	s_and_saveexec_b64 s[8:9], s[4:5]
	s_cbranch_execz .LBB0_518
	v_add_f32_e32 v62, 0x358637bd, v62
	v_rsq_f32_e32 v62, v62
	s_nop 0
	v_mul_f32_e32 v86, v161, v62

.LBB0_520:
	s_or_b64 exec, exec, s[8:9]
	v_pk_fma_f32 v[80:81], v[6:7], v[80:81], 0 op_sel_hi:[1,1,0]
	v_lshlrev_b32_e32 v90, 16, v146
	v_pk_fma_f32 v[80:81], v[10:11], v[78:79], v[80:81]
	v_and_b32_e32 v91, 0xffff0000, v146
	v_pk_fma_f32 v[80:81], v[98:99], v[82:83], v[80:81]
	v_pk_fma_f32 v[66:67], v[8:9], v[66:67], 0 op_sel_hi:[1,1,0]
	v_pk_fma_f32 v[84:85], v[106:107], v[90:91], v[80:81]
	v_pk_fma_f32 v[66:67], v[12:13], v[64:65], v[66:67]
	v_pk_mul_f32 v[226:227], v[84:85], v[246:247] op_sel_hi:[1,0]
	v_exp_f32_e32 v226, v226
	v_exp_f32_e32 v227, v227
	v_lshlrev_b32_e32 v88, 16, v147
	v_pk_add_f32 v[226:227], v[226:227], 1.0 op_sel_hi:[1,0]
	v_rcp_f32_e32 v226, v226
	v_rcp_f32_e32 v227, v227
	v_and_b32_e32 v89, 0xffff0000, v147
	v_pk_fma_f32 v[66:67], v[100:101], v[76:77], v[66:67]
	v_pk_fma_f32 v[72:73], v[2:3], v[72:73], 0 op_sel_hi:[1,1,0]
	v_pk_fma_f32 v[66:67], v[108:109], v[88:89], v[66:67]
	v_pk_mul_f32 v[84:85], v[84:85], v[226:227]
	v_pk_mul_f32 v[226:227], v[66:67], v[246:247] op_sel_hi:[1,0]
	v_exp_f32_e32 v226, v226
	v_exp_f32_e32 v227, v227
	v_pk_fma_f32 v[72:73], v[14:15], v[70:71], v[72:73]
	v_lshlrev_b32_e32 v86, 16, v148
	v_and_b32_e32 v87, 0xffff0000, v148
	v_pk_fma_f32 v[72:73], v[102:103], v[74:75], v[72:73]
	v_pk_fma_f32 v[72:73], v[110:111], v[86:87], v[72:73]
	v_pk_add_f32 v[226:227], v[226:227], 1.0 op_sel_hi:[1,0]
	v_pk_mul_f32 v[228:229], v[72:73], v[246:247] op_sel_hi:[1,0]
	v_rcp_f32_e32 v226, v226
	v_rcp_f32_e32 v227, v227
	v_exp_f32_e32 v228, v228
	v_exp_f32_e32 v229, v229
	v_pk_fma_f32 v[54:55], v[4:5], v[54:55], 0 op_sel_hi:[1,1,0]
	v_lshlrev_b32_e32 v80, 16, v149
	v_pk_fma_f32 v[54:55], v[16:17], v[52:53], v[54:55]
	v_and_b32_e32 v81, 0xffff0000, v149
	v_pk_fma_f32 v[54:55], v[104:105], v[60:61], v[54:55]
	v_pk_mul_f32 v[66:67], v[66:67], v[226:227]
	v_pk_add_f32 v[228:229], v[228:229], 1.0 op_sel_hi:[1,0]
	v_pk_fma_f32 v[96:97], v[112:113], v[80:81], v[54:55]
	v_rcp_f32_e32 v228, v228
	v_pk_mul_f32 v[226:227], v[96:97], v[246:247] op_sel_hi:[1,0]
	v_exp_f32_e32 v226, v226
	v_exp_f32_e32 v227, v227
	v_rcp_f32_e32 v229, v229
	v_pk_add_f32 v[226:227], v[226:227], 1.0 op_sel_hi:[1,0]
	v_rcp_f32_e32 v226, v226
	v_pk_mul_f32 v[234:235], v[84:85], v[84:85]
	v_rcp_f32_e32 v227, v227
	v_pk_fma_f32 v[234:235], v[66:67], v[66:67], v[234:235]
	v_pk_mul_f32 v[54:55], v[72:73], v[228:229]
	v_pk_fma_f32 v[234:235], v[54:55], v[54:55], v[234:235]
	v_pk_mul_f32 v[92:93], v[96:97], v[226:227]
	v_pk_fma_f32 v[234:235], v[92:93], v[92:93], v[234:235]
	v_add_f32_e32 v72, v234, v235
	v_mov_b32_e32 v94, 1.0
	s_nop 1
	v_add_f32_dpp v72, v72, v72 quad_perm:[1,0,3,2] row_mask:0xf bank_mask:0xf
	s_nop 1
	v_add_f32_dpp v72, v72, v72 quad_perm:[2,3,0,1] row_mask:0xf bank_mask:0xf
	s_nop 1
	v_add_f32_dpp v72, v72, v72 row_half_mirror row_mask:0xf bank_mask:0xf
	s_nop 1
	v_add_f32_dpp v72, v72, v72 row_mirror row_mask:0xf bank_mask:0xf
	s_and_saveexec_b64 s[8:9], s[4:5]
	s_cbranch_execz .LBB0_522
	v_add_f32_e32 v72, 0x358637bd, v72
	v_rsq_f32_e32 v72, v72
	s_nop 0
	v_mul_f32_e32 v94, v161, v72

.LBB0_524:
	s_or_b64 exec, exec, s[8:9]
	v_pk_fma_f32 v[78:79], v[6:7], v[78:79], 0 op_sel_hi:[1,1,0]
	v_lshlrev_b32_e32 v162, 16, v150
	v_pk_fma_f32 v[78:79], v[10:11], v[82:83], v[78:79]
	v_and_b32_e32 v163, 0xffff0000, v150
	v_pk_fma_f32 v[78:79], v[98:99], v[90:91], v[78:79]
	v_pk_fma_f32 v[64:65], v[8:9], v[64:65], 0 op_sel_hi:[1,1,0]
	v_pk_fma_f32 v[78:79], v[106:107], v[162:163], v[78:79]
	v_pk_fma_f32 v[64:65], v[12:13], v[76:77], v[64:65]
	v_pk_mul_f32 v[226:227], v[78:79], v[246:247] op_sel_hi:[1,0]
	v_exp_f32_e32 v226, v226
	v_exp_f32_e32 v227, v227
	v_lshlrev_b32_e32 v96, 16, v151
	v_pk_add_f32 v[226:227], v[226:227], 1.0 op_sel_hi:[1,0]
	v_rcp_f32_e32 v226, v226
	v_rcp_f32_e32 v227, v227
	v_and_b32_e32 v97, 0xffff0000, v151
	v_pk_fma_f32 v[64:65], v[100:101], v[88:89], v[64:65]
	v_pk_fma_f32 v[70:71], v[2:3], v[70:71], 0 op_sel_hi:[1,1,0]
	v_pk_fma_f32 v[64:65], v[108:109], v[96:97], v[64:65]
	v_pk_mul_f32 v[78:79], v[78:79], v[226:227]
	v_pk_mul_f32 v[226:227], v[64:65], v[246:247] op_sel_hi:[1,0]
	v_exp_f32_e32 v226, v226
	v_exp_f32_e32 v227, v227
	v_pk_fma_f32 v[70:71], v[14:15], v[74:75], v[70:71]
	v_lshlrev_b32_e32 v94, 16, v152
	v_and_b32_e32 v95, 0xffff0000, v152
	v_pk_fma_f32 v[70:71], v[102:103], v[86:87], v[70:71]
	v_pk_fma_f32 v[70:71], v[110:111], v[94:95], v[70:71]
	v_pk_add_f32 v[226:227], v[226:227], 1.0 op_sel_hi:[1,0]
	v_pk_mul_f32 v[228:229], v[70:71], v[246:247] op_sel_hi:[1,0]
	v_rcp_f32_e32 v226, v226
	v_rcp_f32_e32 v227, v227
	v_exp_f32_e32 v228, v228
	v_pk_fma_f32 v[52:53], v[4:5], v[52:53], 0 op_sel_hi:[1,1,0]
	v_exp_f32_e32 v229, v229
	v_pk_fma_f32 v[52:53], v[16:17], v[60:61], v[52:53]
	v_lshlrev_b32_e32 v92, 16, v153
	v_and_b32_e32 v93, 0xffff0000, v153
	v_pk_fma_f32 v[52:53], v[104:105], v[80:81], v[52:53]
	v_pk_mul_f32 v[64:65], v[64:65], v[226:227]
	v_pk_fma_f32 v[52:53], v[112:113], v[92:93], v[52:53]
	v_pk_mul_f32 v[226:227], v[52:53], v[246:247] op_sel_hi:[1,0]
	v_pk_add_f32 v[228:229], v[228:229], 1.0 op_sel_hi:[1,0]
	v_exp_f32_e32 v226, v226
	v_exp_f32_e32 v227, v227
	v_rcp_f32_e32 v228, v228
	v_rcp_f32_e32 v229, v229
	v_pk_add_f32 v[226:227], v[226:227], 1.0 op_sel_hi:[1,0]
	v_rcp_f32_e32 v226, v226
	v_pk_mul_f32 v[236:237], v[78:79], v[78:79]
	v_rcp_f32_e32 v227, v227
	v_pk_fma_f32 v[236:237], v[64:65], v[64:65], v[236:237]
	v_pk_mul_f32 v[70:71], v[70:71], v[228:229]
	v_pk_fma_f32 v[236:237], v[70:71], v[70:71], v[236:237]
	v_pk_mul_f32 v[164:165], v[52:53], v[226:227]
	v_pk_fma_f32 v[236:237], v[164:165], v[164:165], v[236:237]
	v_add_f32_e32 v52, v236, v237
	v_mov_b32_e32 v166, 1.0
	s_nop 1
	v_add_f32_dpp v52, v52, v52 quad_perm:[1,0,3,2] row_mask:0xf bank_mask:0xf
	s_nop 1
	v_add_f32_dpp v52, v52, v52 quad_perm:[2,3,0,1] row_mask:0xf bank_mask:0xf
	s_nop 1
	v_add_f32_dpp v52, v52, v52 row_half_mirror row_mask:0xf bank_mask:0xf
	s_nop 1
	v_add_f32_dpp v52, v52, v52 row_mirror row_mask:0xf bank_mask:0xf
	s_and_saveexec_b64 s[8:9], s[4:5]
	s_cbranch_execz .LBB0_526
	v_add_f32_e32 v52, 0x358637bd, v52
	v_rsq_f32_e32 v52, v52
	s_nop 0
	v_mul_f32_e32 v166, v161, v52

.LBB0_528:
	s_or_b64 exec, exec, s[8:9]
	v_pk_fma_f32 v[82:83], v[6:7], v[82:83], 0 op_sel_hi:[1,1,0]
	v_pk_fma_f32 v[76:77], v[8:9], v[76:77], 0 op_sel_hi:[1,1,0]
	v_pk_fma_f32 v[82:83], v[10:11], v[90:91], v[82:83]
	v_lshlrev_b32_e32 v90, 16, v154
	v_pk_fma_f32 v[82:83], v[98:99], v[162:163], v[82:83]
	v_and_b32_e32 v91, 0xffff0000, v154
	v_pk_fma_f32 v[82:83], v[106:107], v[90:91], v[82:83]
	v_pk_fma_f32 v[76:77], v[12:13], v[88:89], v[76:77]
	v_pk_mul_f32 v[226:227], v[82:83], v[246:247] op_sel_hi:[1,0]
	v_exp_f32_e32 v226, v226
	v_exp_f32_e32 v227, v227
	v_pk_fma_f32 v[76:77], v[100:101], v[96:97], v[76:77]
	v_lshlrev_b32_e32 v88, 16, v155
	v_pk_add_f32 v[226:227], v[226:227], 1.0 op_sel_hi:[1,0]
	v_rcp_f32_e32 v226, v226
	v_rcp_f32_e32 v227, v227
	v_and_b32_e32 v89, 0xffff0000, v155
	v_pk_fma_f32 v[76:77], v[108:109], v[88:89], v[76:77]
	v_pk_fma_f32 v[74:75], v[2:3], v[74:75], 0 op_sel_hi:[1,1,0]
	v_pk_mul_f32 v[228:229], v[76:77], v[246:247] op_sel_hi:[1,0]
	v_pk_mul_f32 v[82:83], v[82:83], v[226:227]
	v_exp_f32_e32 v228, v228
	v_exp_f32_e32 v229, v229
	v_pk_fma_f32 v[74:75], v[14:15], v[86:87], v[74:75]
	v_lshlrev_b32_e32 v86, 16, v156
	v_pk_fma_f32 v[74:75], v[102:103], v[94:95], v[74:75]
	v_and_b32_e32 v87, 0xffff0000, v156
	v_pk_fma_f32 v[86:87], v[110:111], v[86:87], v[74:75]
	v_pk_fma_f32 v[60:61], v[4:5], v[60:61], 0 op_sel_hi:[1,1,0]
	v_pk_mul_f32 v[226:227], v[86:87], v[246:247] op_sel_hi:[1,0]
	v_pk_fma_f32 v[60:61], v[16:17], v[80:81], v[60:61]
	v_pk_add_f32 v[228:229], v[228:229], 1.0 op_sel_hi:[1,0]
	v_exp_f32_e32 v226, v226
	v_pk_fma_f32 v[60:61], v[104:105], v[92:93], v[60:61]
	v_lshlrev_b32_e32 v80, 16, v157
	v_and_b32_e32 v81, 0xffff0000, v157
	v_rcp_f32_e32 v228, v228
	v_rcp_f32_e32 v229, v229
	v_exp_f32_e32 v227, v227
	v_pk_fma_f32 v[60:61], v[112:113], v[80:81], v[60:61]
	v_pk_mul_f32 v[238:239], v[82:83], v[82:83]
	v_pk_mul_f32 v[230:231], v[60:61], v[246:247] op_sel_hi:[1,0]
	v_exp_f32_e32 v230, v230
	v_exp_f32_e32 v231, v231
	v_pk_mul_f32 v[74:75], v[76:77], v[228:229]
	v_pk_add_f32 v[226:227], v[226:227], 1.0 op_sel_hi:[1,0]
	v_rcp_f32_e32 v226, v226
	v_rcp_f32_e32 v227, v227
	v_pk_add_f32 v[230:231], v[230:231], 1.0 op_sel_hi:[1,0]
	v_rcp_f32_e32 v230, v230
	v_rcp_f32_e32 v231, v231
	v_pk_fma_f32 v[238:239], v[74:75], v[74:75], v[238:239]
	v_pk_mul_f32 v[76:77], v[86:87], v[226:227]
	v_pk_fma_f32 v[238:239], v[76:77], v[76:77], v[238:239]
	v_pk_mul_f32 v[80:81], v[60:61], v[230:231]
	v_pk_fma_f32 v[238:239], v[80:81], v[80:81], v[238:239]
	v_add_f32_e32 v60, v238, v239
	v_mov_b32_e32 v86, 1.0
	s_nop 1
	v_add_f32_dpp v19, v60, v60 quad_perm:[1,0,3,2] row_mask:0xf bank_mask:0xf
	s_nop 1
	v_add_f32_dpp v19, v19, v19 quad_perm:[2,3,0,1] row_mask:0xf bank_mask:0xf
	s_nop 1
	v_add_f32_dpp v19, v19, v19 row_half_mirror row_mask:0xf bank_mask:0xf
	s_nop 1
	v_add_f32_dpp v19, v19, v19 row_mirror row_mask:0xf bank_mask:0xf
	s_and_saveexec_b64 s[8:9], s[4:5]
	s_cbranch_execz .LBB0_530
	v_add_f32_e32 v19, 0x358637bd, v19
	v_rsq_f32_e32 v19, v19
	s_nop 0
	v_mul_f32_e32 v86, v161, v19

.LBB0_1023:
	s_lshl_b32 s4, s4, 5
	s_and_b32 s14, s4, 0x60
	s_mov_b64 s[4:5], 0x80
	s_add_i32 m0, s31, 0x18000
	v_lshl_add_u64 v[8:9], v[8:9], 0, s[4:5]
	s_lshl_b32 s7, s1, 13
	s_lshl_b32 s12, s14, 7
	s_waitcnt vmcnt(2)
	s_barrier
	global_load_lds_dwordx4 v[8:9], off
	v_lshl_add_u64 v[6:7], v[6:7], 0, s[4:5]
	s_add_i32 m0, s31, 0x1a000
	s_add_i32 s46, s31, 0x8000
	s_add_i32 s47, s31, 0xa000
	global_load_lds_dwordx4 v[6:7], off
	v_lshl_add_u64 v[4:5], v[4:5], 0, s[4:5]
	s_mov_b32 m0, s46
	s_add_u32 s10, s36, 0x80080
	global_load_lds_dwordx4 v[4:5], off
	v_lshl_add_u64 v[2:3], v[2:3], 0, s[4:5]
	s_mov_b32 m0, s47
	s_addc_u32 s11, s37, 0
	global_load_lds_dwordx4 v[2:3], off
	s_add_i32 m0, s31, 0x1c000
	v_lshl_add_u64 v[2:3], s[10:11], 0, v[128:129]
	global_load_lds_dwordx4 v[2:3], off
	v_lshl_add_u64 v[2:3], s[10:11], 0, v[130:131]
	s_add_i32 m0, s31, 0x1e000
	v_lshlrev_b32_e32 v5, 2, v0
	global_load_lds_dwordx4 v[2:3], off
	v_and_b32_e32 v2, 15, v0
	v_lshrrev_b32_e32 v246, 6, v0
	v_lshrrev_b32_e32 v247, 3, v2
	v_lshl_add_u32 v246, v246, 1, v247
	v_and_b32_e32 v247, 7, v2
	v_lshlrev_b32_e32 v247, 7, v247
	v_lshl_add_u32 v247, v246, 13, v247
	v_bfe_u32 v3, v0, 4, 2
	v_lshlrev_b32_e32 v6, 6, v0
	v_lshlrev_b32_e32 v0, 9, v0
	v_lshlrev_b32_e32 v4, 4, v3
	v_readlane_b32 s64, v249, 12
	v_lshl_or_b32 v150, v3, 2, s14
	v_and_b32_e32 v0, 0x30000, v0
	v_lshlrev_b32_e32 v3, 12, v11
	s_sext_i32_i8 s51, s0
	v_lshl_or_b32 v148, s1, 6, v2
	v_lshl_or_b32 v2, v2, 6, v4
	v_and_b32_e32 v5, 32, v5
	s_movk_i32 s0, 0x3c0
	s_cmpk_lt_u32 s6, 0x100
	v_readlane_b32 s72, v249, 20
	v_readlane_b32 s73, v249, 21
	v_or3_b32 v0, v1, v0, v3
	v_bitop3_b32 v2, v2, s7, v5 bitop3:0xde
	v_and_or_b32 v4, v6, s0, v4
	s_cselect_b64 s[6:7], -1, 0
	s_ashr_i32 s48, s81, 31
	s_mov_b64 s[20:21], s[72:73]
	v_add_u32_e32 v132, v0, v10
	v_lshlrev_b32_e32 v0, 5, v12
	v_bitop3_b32 v149, s12, v4, v5 bitop3:0xf6
	s_waitcnt vmcnt(6)
	s_add_u32 s12, s20, 0x4000
	v_and_b32_e32 v0, 0x70000, v0
	s_addc_u32 s13, s21, 0
	v_or3_b32 v0, v1, v0, v3
	s_add_i32 s49, 0, 0x10000
	s_add_i32 s50, 0, 0x14000
	s_mov_b64 s[10:11], 0x4000
	v_mov_b32_e32 v133, v129
	v_add_u32_e32 v134, v0, v10
	v_mov_b32_e32 v135, v129
	v_mov_b64_e32 v[136:137], 0x100
	v_mov_b64_e32 v[138:139], 0xff
	v_add_u32_e32 v151, s49, v149
	v_add_u32_e32 v152, s50, v149
	v_add_u32_e32 v153, 0, v2
	s_mov_b64 s[14:15], 0x100000
	s_mov_b64 s[16:17], 0x120000
	s_mov_b64 s[18:19], 0x140000
	s_mov_b64 s[20:21], 0x160000
	s_barrier
	v_readlane_b32 s65, v249, 13
	v_readlane_b32 s66, v249, 14
	v_readlane_b32 s67, v249, 15
	v_readlane_b32 s68, v249, 16
	v_readlane_b32 s69, v249, 17
	v_readlane_b32 s70, v249, 18
	v_readlane_b32 s71, v249, 19
	v_readlane_b32 s74, v249, 22
	v_readlane_b32 s75, v249, 23
	v_readlane_b32 s76, v249, 24
	v_readlane_b32 s77, v249, 25
	v_readlane_b32 s78, v249, 26
	v_readlane_b32 s79, v249, 27
	s_branch .LBB0_1026

.LBB0_1032:
	s_ashr_i32 s25, s24, 31
	s_lshl_b64 s[26:27], s[24:25], 20
	s_add_u32 s26, s8, s26
	s_addc_u32 s27, s9, s27
	s_and_b64 s[28:29], s[0:1], exec
	s_cselect_b32 s25, s27, s35
	s_cselect_b32 s52, s26, s34
	s_ashr_i32 s23, s22, 31
	s_lshl_b64 s[28:29], s[22:23], 20
	v_readlane_b32 s38, v249, 39
	v_readlane_b32 s39, v249, 40
	s_add_u32 s28, s38, s28
	s_addc_u32 s29, s39, s29
	s_and_b64 s[38:39], s[0:1], exec
	s_cselect_b32 s23, s29, s37
	s_cselect_b32 s53, s28, s36
	s_add_u32 s34, s34, 0x80080
	s_addc_u32 s35, s35, 0
	s_add_u32 s54, s36, 0x100
	v_mov_b32_e32 v0, 0
	s_addc_u32 s55, s37, 0
	s_mov_b32 s56, -2
	s_lshl_b32 s98, s30, 21
	s_lshl_b32 s99, s51, 10
	s_add_i32 s98, s98, s99
	v_readlane_b32 s100, v249, 12
	v_readlane_b32 s101, v249, 13
	v_add_u32_e32 v246, s98, v247
	v_mov_b32_e32 v1, v0
	v_mov_b32_e32 v2, v0
	v_mov_b32_e32 v3, v0
	v_mov_b32_e32 v4, v0
	v_mov_b32_e32 v5, v0
	v_mov_b32_e32 v6, v0
	v_mov_b32_e32 v7, v0
	v_mov_b32_e32 v8, v0
	v_mov_b32_e32 v9, v0
	v_mov_b32_e32 v10, v0
	v_mov_b32_e32 v11, v0
	v_mov_b32_e32 v20, v0
	v_mov_b32_e32 v21, v0
	v_mov_b32_e32 v22, v0
	v_mov_b32_e32 v23, v0
	v_mov_b32_e32 v24, v0
	v_mov_b32_e32 v25, v0
	v_mov_b32_e32 v26, v0
	v_mov_b32_e32 v27, v0
	v_mov_b32_e32 v36, v0
	v_mov_b32_e32 v37, v0
	v_mov_b32_e32 v38, v0
	v_mov_b32_e32 v39, v0
	v_mov_b32_e32 v40, v0
	v_mov_b32_e32 v41, v0
	v_mov_b32_e32 v42, v0
	v_mov_b32_e32 v43, v0
	v_mov_b32_e32 v52, v0
	v_mov_b32_e32 v53, v0
	v_mov_b32_e32 v54, v0
	v_mov_b32_e32 v55, v0
	v_mov_b32_e32 v12, v0
	v_mov_b32_e32 v13, v0
	v_mov_b32_e32 v14, v0
	v_mov_b32_e32 v15, v0
	v_mov_b32_e32 v16, v0
	v_mov_b32_e32 v17, v0
	v_mov_b32_e32 v18, v0
	v_mov_b32_e32 v19, v0
	v_mov_b32_e32 v28, v0
	v_mov_b32_e32 v29, v0
	v_mov_b32_e32 v30, v0
	v_mov_b32_e32 v31, v0
	v_mov_b32_e32 v32, v0
	v_mov_b32_e32 v33, v0
	v_mov_b32_e32 v34, v0
	v_mov_b32_e32 v35, v0
	v_mov_b32_e32 v44, v0
	v_mov_b32_e32 v45, v0
	v_mov_b32_e32 v46, v0
	v_mov_b32_e32 v47, v0
	v_mov_b32_e32 v48, v0
	v_mov_b32_e32 v49, v0
	v_mov_b32_e32 v50, v0
	v_mov_b32_e32 v51, v0
	v_mov_b32_e32 v56, v0
	v_mov_b32_e32 v57, v0
	v_mov_b32_e32 v58, v0
	v_mov_b32_e32 v59, v0
	v_mov_b32_e32 v60, v0
	v_mov_b32_e32 v61, v0
	v_mov_b32_e32 v62, v0
	v_mov_b32_e32 v63, v0
	v_mov_b32_e32 v64, v0
	v_mov_b32_e32 v65, v0
	v_mov_b32_e32 v66, v0
	v_mov_b32_e32 v67, v0
	v_mov_b32_e32 v68, v0
	v_mov_b32_e32 v69, v0
	v_mov_b32_e32 v70, v0
	v_mov_b32_e32 v71, v0
	v_mov_b32_e32 v72, v0
	v_mov_b32_e32 v73, v0
	v_mov_b32_e32 v74, v0
	v_mov_b32_e32 v75, v0
	v_mov_b32_e32 v84, v0
	v_mov_b32_e32 v85, v0
	v_mov_b32_e32 v86, v0
	v_mov_b32_e32 v87, v0
	v_mov_b32_e32 v88, v0
	v_mov_b32_e32 v89, v0
	v_mov_b32_e32 v90, v0
	v_mov_b32_e32 v91, v0
	v_mov_b32_e32 v100, v0
	v_mov_b32_e32 v101, v0
	v_mov_b32_e32 v102, v0
	v_mov_b32_e32 v103, v0
	v_mov_b32_e32 v104, v0
	v_mov_b32_e32 v105, v0
	v_mov_b32_e32 v106, v0
	v_mov_b32_e32 v107, v0
	v_mov_b32_e32 v116, v0
	v_mov_b32_e32 v117, v0
	v_mov_b32_e32 v118, v0
	v_mov_b32_e32 v119, v0
	v_mov_b32_e32 v76, v0
	v_mov_b32_e32 v77, v0
	v_mov_b32_e32 v78, v0
	v_mov_b32_e32 v79, v0
	v_mov_b32_e32 v80, v0
	v_mov_b32_e32 v81, v0
	v_mov_b32_e32 v82, v0
	v_mov_b32_e32 v83, v0
	v_mov_b32_e32 v92, v0
	v_mov_b32_e32 v93, v0
	v_mov_b32_e32 v94, v0
	v_mov_b32_e32 v95, v0
	v_mov_b32_e32 v96, v0
	v_mov_b32_e32 v97, v0
	v_mov_b32_e32 v98, v0
	v_mov_b32_e32 v99, v0
	v_mov_b32_e32 v108, v0
	v_mov_b32_e32 v109, v0
	v_mov_b32_e32 v110, v0
	v_mov_b32_e32 v111, v0
	v_mov_b32_e32 v112, v0
	v_mov_b32_e32 v113, v0
	v_mov_b32_e32 v114, v0
	v_mov_b32_e32 v115, v0
	v_mov_b32_e32 v120, v0
	v_mov_b32_e32 v121, v0
	v_mov_b32_e32 v122, v0
	v_mov_b32_e32 v123, v0
	v_mov_b32_e32 v124, v0
	v_mov_b32_e32 v125, v0
	v_mov_b32_e32 v126, v0
	v_mov_b32_e32 v127, v0
.LBB0_1033:
	ds_read_b128 v[140:143], v151
	ds_read_b128 v[144:147], v151 offset:1024
	ds_read_b128 v[154:157], v151 offset:2048
	ds_read_b128 v[158:161], v151 offset:3072
	ds_read_b128 v[162:165], v152
	ds_read_b128 v[166:169], v152 offset:1024
	ds_read_b128 v[170:173], v152 offset:2048
	ds_read_b128 v[174:177], v152 offset:3072
	s_add_u32 s36, s34, 0xfff80080
	s_addc_u32 s37, s35, -1
	s_cmp_eq_u32 s56, 28
	s_cselect_b32 s39, s25, s37
	s_cselect_b32 s38, s52, s36
	s_cselect_b32 s37, s23, s55
	s_cselect_b32 s36, s53, s54
	v_lshl_add_u64 v[210:211], s[34:35], 0, v[132:133]
	s_add_i32 m0, s31, 0xc000
	ds_read_b128 v[178:181], v153
	ds_read_b128 v[182:185], v153 offset:1024
	ds_read_b128 v[186:189], v153 offset:2048
	ds_read_b128 v[190:193], v153 offset:3072
	ds_read_b128 v[194:197], v153 offset:4096
	ds_read_b128 v[198:201], v153 offset:5120
	ds_read_b128 v[202:205], v153 offset:6144
	ds_read_b128 v[206:209], v153 offset:7168
	s_mov_b64 exec, 0xffff
	global_load_dword v248, v246, s[100:101]
	s_mov_b64 exec, -1
	v_add_u32_e32 v246, 0x20000, v246
	global_load_lds_dwordx4 v[210:211], off
	v_lshl_add_u64 v[210:211], s[34:35], 0, v[134:135]
	s_add_i32 m0, s31, 0xe000
	s_nop 0
	global_load_lds_dwordx4 v[210:211], off
	s_waitcnt vmcnt(9)
	s_waitcnt lgkmcnt(0)
	s_barrier
	s_setprio 1
	s_waitcnt lgkmcnt(0)
	v_mfma_f32_16x16x32_bf16 v[124:127], v[140:143], v[178:181], v[124:127]
	v_mfma_f32_16x16x32_bf16 v[120:123], v[154:157], v[178:181], v[120:123]
	v_mfma_f32_16x16x32_bf16 v[112:115], v[140:143], v[186:189], v[112:115]
	v_mfma_f32_16x16x32_bf16 v[108:111], v[154:157], v[186:189], v[108:111]
	v_mfma_f32_16x16x32_bf16 v[96:99], v[140:143], v[194:197], v[96:99]
	v_mfma_f32_16x16x32_bf16 v[92:95], v[154:157], v[194:197], v[92:95]
	v_mfma_f32_16x16x32_bf16 v[80:83], v[140:143], v[202:205], v[80:83]
	v_mfma_f32_16x16x32_bf16 v[76:79], v[154:157], v[202:205], v[76:79]
	v_mfma_f32_16x16x32_bf16 v[124:127], v[144:147], v[182:185], v[124:127]
	v_mfma_f32_16x16x32_bf16 v[120:123], v[158:161], v[182:185], v[120:123]
	v_mfma_f32_16x16x32_bf16 v[112:115], v[144:147], v[190:193], v[112:115]
	v_mfma_f32_16x16x32_bf16 v[108:111], v[158:161], v[190:193], v[108:111]
	v_mfma_f32_16x16x32_bf16 v[96:99], v[144:147], v[198:201], v[96:99]
	v_mfma_f32_16x16x32_bf16 v[92:95], v[158:161], v[198:201], v[92:95]
	v_mfma_f32_16x16x32_bf16 v[80:83], v[144:147], v[206:209], v[80:83]
	v_mfma_f32_16x16x32_bf16 v[76:79], v[158:161], v[206:209], v[76:79]
	s_setprio 0
	s_setprio 1
	v_mfma_f32_16x16x32_bf16 v[116:119], v[162:165], v[178:181], v[116:119]
	v_mfma_f32_16x16x32_bf16 v[104:107], v[170:173], v[178:181], v[104:107]
	v_mfma_f32_16x16x32_bf16 v[100:103], v[162:165], v[186:189], v[100:103]
	v_mfma_f32_16x16x32_bf16 v[88:91], v[170:173], v[186:189], v[88:91]
	v_mfma_f32_16x16x32_bf16 v[84:87], v[162:165], v[194:197], v[84:87]
	v_mfma_f32_16x16x32_bf16 v[72:75], v[170:173], v[194:197], v[72:75]
	v_mfma_f32_16x16x32_bf16 v[68:71], v[162:165], v[202:205], v[68:71]
	v_mfma_f32_16x16x32_bf16 v[64:67], v[170:173], v[202:205], v[64:67]
	v_mfma_f32_16x16x32_bf16 v[116:119], v[166:169], v[182:185], v[116:119]
	v_mfma_f32_16x16x32_bf16 v[104:107], v[174:177], v[182:185], v[104:107]
	v_mfma_f32_16x16x32_bf16 v[100:103], v[166:169], v[190:193], v[100:103]
	v_mfma_f32_16x16x32_bf16 v[88:91], v[174:177], v[190:193], v[88:91]
	v_mfma_f32_16x16x32_bf16 v[84:87], v[166:169], v[198:201], v[84:87]
	v_mfma_f32_16x16x32_bf16 v[72:75], v[174:177], v[198:201], v[72:75]
	v_mfma_f32_16x16x32_bf16 v[68:71], v[166:169], v[206:209], v[68:71]
	v_mfma_f32_16x16x32_bf16 v[64:67], v[174:177], v[206:209], v[64:67]
	s_setprio 0
	s_barrier
	s_add_i32 s57, s49, s40
	v_lshl_add_u64 v[210:211], s[36:37], 0, v[128:129]
	s_mov_b32 m0, s57
	ds_read_b128 v[178:181], v153 offset:16384
	ds_read_b128 v[182:185], v153 offset:17408
	ds_read_b128 v[186:189], v153 offset:18432
	ds_read_b128 v[190:193], v153 offset:19456
	ds_read_b128 v[194:197], v153 offset:20480
	ds_read_b128 v[198:201], v153 offset:21504
	ds_read_b128 v[202:205], v153 offset:22528
	ds_read_b128 v[206:209], v153 offset:23552
	global_load_lds_dwordx4 v[210:211], off
	s_add_i32 m0, s57, 0x2000
	s_add_u32 s58, s36, 0x80000
	v_lshl_add_u64 v[212:213], s[36:37], 0, v[130:131]
	s_addc_u32 s59, s37, 0
	s_add_i32 s57, s50, s40
	global_load_lds_dwordx4 v[212:213], off
	v_lshl_add_u64 v[214:215], s[58:59], 0, v[128:129]
	s_mov_b32 m0, s57
	v_lshl_add_u64 v[216:217], s[38:39], 0, v[130:131]
	global_load_lds_dwordx4 v[214:215], off
	v_lshl_add_u64 v[214:215], s[58:59], 0, v[130:131]
	s_add_i32 m0, s57, 0x2000
	s_nop 0
	global_load_lds_dwordx4 v[214:215], off
	v_lshl_add_u64 v[214:215], s[38:39], 0, v[128:129]
	s_mov_b32 m0, s31
	s_nop 0
	global_load_lds_dwordx4 v[214:215], off
	s_mov_b32 m0, s41
	s_nop 0
	global_load_lds_dwordx4 v[216:217], off
	s_waitcnt vmcnt(9)
	s_waitcnt lgkmcnt(0)
	s_barrier
	s_setprio 1
	s_waitcnt lgkmcnt(0)
	v_mfma_f32_16x16x32_bf16 v[60:63], v[140:143], v[178:181], v[60:63]
	v_mfma_f32_16x16x32_bf16 v[56:59], v[154:157], v[178:181], v[56:59]
	v_mfma_f32_16x16x32_bf16 v[48:51], v[140:143], v[186:189], v[48:51]
	v_mfma_f32_16x16x32_bf16 v[44:47], v[154:157], v[186:189], v[44:47]
	v_mfma_f32_16x16x32_bf16 v[32:35], v[140:143], v[194:197], v[32:35]
	v_mfma_f32_16x16x32_bf16 v[28:31], v[154:157], v[194:197], v[28:31]
	v_mfma_f32_16x16x32_bf16 v[16:19], v[140:143], v[202:205], v[16:19]
	v_mfma_f32_16x16x32_bf16 v[12:15], v[154:157], v[202:205], v[12:15]
	v_mfma_f32_16x16x32_bf16 v[60:63], v[144:147], v[182:185], v[60:63]
	v_mfma_f32_16x16x32_bf16 v[56:59], v[158:161], v[182:185], v[56:59]
	v_mfma_f32_16x16x32_bf16 v[48:51], v[144:147], v[190:193], v[48:51]
	v_mfma_f32_16x16x32_bf16 v[44:47], v[158:161], v[190:193], v[44:47]
	v_mfma_f32_16x16x32_bf16 v[32:35], v[144:147], v[198:201], v[32:35]
	v_mfma_f32_16x16x32_bf16 v[28:31], v[158:161], v[198:201], v[28:31]
	v_mfma_f32_16x16x32_bf16 v[16:19], v[144:147], v[206:209], v[16:19]
	v_mfma_f32_16x16x32_bf16 v[12:15], v[158:161], v[206:209], v[12:15]
	s_setprio 0
	s_setprio 1
	v_mfma_f32_16x16x32_bf16 v[52:55], v[162:165], v[178:181], v[52:55]
	v_mfma_f32_16x16x32_bf16 v[40:43], v[170:173], v[178:181], v[40:43]
	v_mfma_f32_16x16x32_bf16 v[36:39], v[162:165], v[186:189], v[36:39]
	v_mfma_f32_16x16x32_bf16 v[24:27], v[170:173], v[186:189], v[24:27]
	v_mfma_f32_16x16x32_bf16 v[20:23], v[162:165], v[194:197], v[20:23]
	v_mfma_f32_16x16x32_bf16 v[8:11], v[170:173], v[194:197], v[8:11]
	v_mfma_f32_16x16x32_bf16 v[4:7], v[162:165], v[202:205], v[4:7]
	v_mfma_f32_16x16x32_bf16 v[0:3], v[170:173], v[202:205], v[0:3]
	v_mfma_f32_16x16x32_bf16 v[52:55], v[166:169], v[182:185], v[52:55]
	v_mfma_f32_16x16x32_bf16 v[40:43], v[174:177], v[182:185], v[40:43]
	v_mfma_f32_16x16x32_bf16 v[36:39], v[166:169], v[190:193], v[36:39]
	v_mfma_f32_16x16x32_bf16 v[24:27], v[174:177], v[190:193], v[24:27]
	v_mfma_f32_16x16x32_bf16 v[20:23], v[166:169], v[198:201], v[20:23]
	v_mfma_f32_16x16x32_bf16 v[8:11], v[174:177], v[198:201], v[8:11]
	v_mfma_f32_16x16x32_bf16 v[4:7], v[166:169], v[206:209], v[4:7]
	v_mfma_f32_16x16x32_bf16 v[0:3], v[174:177], v[206:209], v[0:3]
	s_setprio 0
	s_barrier
	s_add_i32 s57, 0, 0x18000
	s_add_i32 s58, 0, 0x1c000
	v_add_u32_e32 v158, s57, v149
	v_add_u32_e32 v174, s58, v149
	ds_read_b128 v[140:143], v158
	ds_read_b128 v[144:147], v158 offset:1024
	ds_read_b128 v[154:157], v158 offset:2048
	ds_read_b128 v[158:161], v158 offset:3072
	ds_read_b128 v[162:165], v174
	ds_read_b128 v[166:169], v174 offset:1024
	ds_read_b128 v[170:173], v174 offset:2048
	ds_read_b128 v[174:177], v174 offset:3072
	s_add_u32 s38, s38, 0x80000
	s_addc_u32 s39, s39, 0
	s_mov_b32 m0, s42
	v_lshl_add_u64 v[218:219], s[38:39], 0, v[128:129]
	ds_read_b128 v[178:181], v153 offset:32768
	ds_read_b128 v[182:185], v153 offset:33792
	ds_read_b128 v[186:189], v153 offset:34816
	ds_read_b128 v[190:193], v153 offset:35840
	ds_read_b128 v[194:197], v153 offset:36864
	ds_read_b128 v[198:201], v153 offset:37888
	ds_read_b128 v[202:205], v153 offset:38912
	ds_read_b128 v[206:209], v153 offset:39936
	global_load_lds_dwordx4 v[218:219], off
	v_lshl_add_u64 v[218:219], s[38:39], 0, v[130:131]
	s_mov_b32 m0, s43
	s_nop 0
	global_load_lds_dwordx4 v[218:219], off
	s_waitcnt vmcnt(8)
	s_waitcnt lgkmcnt(0)
	s_barrier
	s_setprio 1
	s_waitcnt lgkmcnt(0)
	v_mfma_f32_16x16x32_bf16 v[124:127], v[140:143], v[178:181], v[124:127]
	v_mfma_f32_16x16x32_bf16 v[120:123], v[154:157], v[178:181], v[120:123]
	v_mfma_f32_16x16x32_bf16 v[112:115], v[140:143], v[186:189], v[112:115]
	v_mfma_f32_16x16x32_bf16 v[108:111], v[154:157], v[186:189], v[108:111]
	v_mfma_f32_16x16x32_bf16 v[96:99], v[140:143], v[194:197], v[96:99]
	v_mfma_f32_16x16x32_bf16 v[92:95], v[154:157], v[194:197], v[92:95]
	v_mfma_f32_16x16x32_bf16 v[80:83], v[140:143], v[202:205], v[80:83]
	v_mfma_f32_16x16x32_bf16 v[76:79], v[154:157], v[202:205], v[76:79]
	v_mfma_f32_16x16x32_bf16 v[124:127], v[144:147], v[182:185], v[124:127]
	v_mfma_f32_16x16x32_bf16 v[120:123], v[158:161], v[182:185], v[120:123]
	v_mfma_f32_16x16x32_bf16 v[112:115], v[144:147], v[190:193], v[112:115]
	v_mfma_f32_16x16x32_bf16 v[108:111], v[158:161], v[190:193], v[108:111]
	v_mfma_f32_16x16x32_bf16 v[96:99], v[144:147], v[198:201], v[96:99]
	v_mfma_f32_16x16x32_bf16 v[92:95], v[158:161], v[198:201], v[92:95]
	v_mfma_f32_16x16x32_bf16 v[80:83], v[144:147], v[206:209], v[80:83]
	v_mfma_f32_16x16x32_bf16 v[76:79], v[158:161], v[206:209], v[76:79]
	s_setprio 0
	s_setprio 1
	v_mfma_f32_16x16x32_bf16 v[116:119], v[162:165], v[178:181], v[116:119]
	v_mfma_f32_16x16x32_bf16 v[104:107], v[170:173], v[178:181], v[104:107]
	v_mfma_f32_16x16x32_bf16 v[100:103], v[162:165], v[186:189], v[100:103]
	v_mfma_f32_16x16x32_bf16 v[88:91], v[170:173], v[186:189], v[88:91]
	v_mfma_f32_16x16x32_bf16 v[84:87], v[162:165], v[194:197], v[84:87]
	v_mfma_f32_16x16x32_bf16 v[72:75], v[170:173], v[194:197], v[72:75]
	v_mfma_f32_16x16x32_bf16 v[68:71], v[162:165], v[202:205], v[68:71]
	v_mfma_f32_16x16x32_bf16 v[64:67], v[170:173], v[202:205], v[64:67]
	v_mfma_f32_16x16x32_bf16 v[116:119], v[166:169], v[182:185], v[116:119]
	v_mfma_f32_16x16x32_bf16 v[104:107], v[174:177], v[182:185], v[104:107]
	v_mfma_f32_16x16x32_bf16 v[100:103], v[166:169], v[190:193], v[100:103]
	v_mfma_f32_16x16x32_bf16 v[88:91], v[174:177], v[190:193], v[88:91]
	v_mfma_f32_16x16x32_bf16 v[84:87], v[166:169], v[198:201], v[84:87]
	v_mfma_f32_16x16x32_bf16 v[72:75], v[174:177], v[198:201], v[72:75]
	v_mfma_f32_16x16x32_bf16 v[68:71], v[166:169], v[206:209], v[68:71]
	v_mfma_f32_16x16x32_bf16 v[64:67], v[174:177], v[206:209], v[64:67]
	s_setprio 0
	s_barrier
	s_add_i32 s38, s57, s40
	v_lshl_add_u64 v[210:211], v[210:211], 0, s[4:5]
	s_mov_b32 m0, s38
	ds_read_b128 v[178:181], v153 offset:49152
	ds_read_b128 v[182:185], v153 offset:50176
	ds_read_b128 v[186:189], v153 offset:51200
	ds_read_b128 v[190:193], v153 offset:52224
	ds_read_b128 v[194:197], v153 offset:53248
	ds_read_b128 v[198:201], v153 offset:54272
	ds_read_b128 v[202:205], v153 offset:55296
	ds_read_b128 v[206:209], v153 offset:56320
	global_load_lds_dwordx4 v[210:211], off
	s_add_i32 m0, s38, 0x2000
	s_add_u32 s36, s36, 0x80080
	v_lshl_add_u64 v[210:211], v[212:213], 0, s[4:5]
	s_addc_u32 s37, s37, 0
	s_add_i32 s38, s58, s40
	global_load_lds_dwordx4 v[210:211], off
	v_lshl_add_u64 v[210:211], s[36:37], 0, v[128:129]
	s_mov_b32 m0, s38
	s_nop 0
	global_load_lds_dwordx4 v[210:211], off
	v_lshl_add_u64 v[210:211], s[36:37], 0, v[130:131]
	s_add_i32 m0, s38, 0x2000
	s_nop 0
	global_load_lds_dwordx4 v[210:211], off
	v_lshl_add_u64 v[210:211], v[214:215], 0, s[4:5]
	s_mov_b32 m0, s46
	s_nop 0
	global_load_lds_dwordx4 v[210:211], off
	v_lshl_add_u64 v[210:211], v[216:217], 0, s[4:5]
	s_mov_b32 m0, s47
	s_nop 0
	global_load_lds_dwordx4 v[210:211], off
	s_waitcnt vmcnt(8)
	s_waitcnt lgkmcnt(0)
	s_barrier
	s_setprio 1
	s_waitcnt lgkmcnt(0)
	v_mfma_f32_16x16x32_bf16 v[60:63], v[140:143], v[178:181], v[60:63]
	v_mfma_f32_16x16x32_bf16 v[56:59], v[154:157], v[178:181], v[56:59]
	v_mfma_f32_16x16x32_bf16 v[48:51], v[140:143], v[186:189], v[48:51]
	v_mfma_f32_16x16x32_bf16 v[44:47], v[154:157], v[186:189], v[44:47]
	v_mfma_f32_16x16x32_bf16 v[32:35], v[140:143], v[194:197], v[32:35]
	v_mfma_f32_16x16x32_bf16 v[28:31], v[154:157], v[194:197], v[28:31]
	v_mfma_f32_16x16x32_bf16 v[16:19], v[140:143], v[202:205], v[16:19]
	v_mfma_f32_16x16x32_bf16 v[12:15], v[154:157], v[202:205], v[12:15]
	v_mfma_f32_16x16x32_bf16 v[60:63], v[144:147], v[182:185], v[60:63]
	v_mfma_f32_16x16x32_bf16 v[56:59], v[158:161], v[182:185], v[56:59]
	v_mfma_f32_16x16x32_bf16 v[48:51], v[144:147], v[190:193], v[48:51]
	v_mfma_f32_16x16x32_bf16 v[44:47], v[158:161], v[190:193], v[44:47]
	v_mfma_f32_16x16x32_bf16 v[32:35], v[144:147], v[198:201], v[32:35]
	v_mfma_f32_16x16x32_bf16 v[28:31], v[158:161], v[198:201], v[28:31]
	v_mfma_f32_16x16x32_bf16 v[16:19], v[144:147], v[206:209], v[16:19]
	v_mfma_f32_16x16x32_bf16 v[12:15], v[158:161], v[206:209], v[12:15]
	s_setprio 0
	s_setprio 1
	v_mfma_f32_16x16x32_bf16 v[52:55], v[162:165], v[178:181], v[52:55]
	v_mfma_f32_16x16x32_bf16 v[40:43], v[170:173], v[178:181], v[40:43]
	v_mfma_f32_16x16x32_bf16 v[36:39], v[162:165], v[186:189], v[36:39]
	v_mfma_f32_16x16x32_bf16 v[24:27], v[170:173], v[186:189], v[24:27]
	v_mfma_f32_16x16x32_bf16 v[20:23], v[162:165], v[194:197], v[20:23]
	v_mfma_f32_16x16x32_bf16 v[8:11], v[170:173], v[194:197], v[8:11]
	v_mfma_f32_16x16x32_bf16 v[4:7], v[162:165], v[202:205], v[4:7]
	v_mfma_f32_16x16x32_bf16 v[0:3], v[170:173], v[202:205], v[0:3]
	v_mfma_f32_16x16x32_bf16 v[52:55], v[166:169], v[182:185], v[52:55]
	v_mfma_f32_16x16x32_bf16 v[40:43], v[174:177], v[182:185], v[40:43]
	v_mfma_f32_16x16x32_bf16 v[36:39], v[166:169], v[190:193], v[36:39]
	v_mfma_f32_16x16x32_bf16 v[24:27], v[174:177], v[190:193], v[24:27]
	v_mfma_f32_16x16x32_bf16 v[20:23], v[166:169], v[198:201], v[20:23]
	v_mfma_f32_16x16x32_bf16 v[8:11], v[174:177], v[198:201], v[8:11]
	v_mfma_f32_16x16x32_bf16 v[4:7], v[166:169], v[206:209], v[4:7]
	v_mfma_f32_16x16x32_bf16 v[0:3], v[174:177], v[206:209], v[0:3]
	s_setprio 0
	s_barrier
	s_add_i32 s56, s56, 2
	s_add_u32 s34, s34, 0x100
	s_addc_u32 s35, s35, 0
	s_add_u32 s54, s54, 0x100
	s_addc_u32 s55, s55, 0
	s_cmp_gt_u32 s56, 29
	s_cbranch_scc0 .LBB0_1033
	s_and_b64 vcc, exec, s[6:7]
	s_cbranch_vccz .LBB0_1036
	s_barrier
